# grid barrier protocol restructured: 8 wgid shards, per-shard arrival counter, top counter, global-last arriver bumps the 8 release words (leader relay hop removed)
# speedup vs baseline: 1.0051x; 1.0051x over previous
_Z6mk_fwd4Args:
	s_mov_b32 s100, 0
	s_add_u32 s4, s0, 0xa0
	s_load_dword s3, s[0:1], 0xa0
	s_addc_u32 s5, s1, 0
	v_mov_b32_e32 v2, v0
	v_writelane_b32 v253, s4, 0
	s_nop 1
	v_writelane_b32 v253, s5, 1
	s_movk_i32 s4, 0x400
	v_cmp_gt_i32_e32 vcc, s4, v2
	s_and_saveexec_b64 s[4:5], vcc
	s_cbranch_execz .LBB0_3
	v_add_u32_e32 v1, 0xfffffe00, v2
	v_lshl_add_u32 v2, v2, 2, 0
	v_add_u32_e32 v2, 0x23000, v2
	s_mov_b64 s[6:7], 0
	v_mov_b32_e32 v3, 0
	s_movk_i32 s8, 0x1ff

.LBB0_130:
	s_or_b64 exec, exec, s[0:1]
	s_getreg_b32 s0, hwreg(HW_REG_XCC_ID, 0, 4)
	s_and_b32 s48, s0, 15
	s_waitcnt vmcnt(0)
	s_barrier
	s_and_saveexec_b64 s[0:1], s[52:53]
	s_add_i32 s100, s100, 1
	s_cbranch_execz .LBB0_182
	v_readlane_b32 s98, v253, 2
	v_readlane_b32 s99, v253, 3
	s_nop 0
	s_add_u32 s98, s98, 0x7c000
	s_addc_u32 s99, s99, 0
	s_and_b32 s101, s2, 7
	s_sub_u32 vcc_lo, 7, s101
	s_add_u32 vcc_lo, vcc_lo, s3
	s_lshr_b32 vcc_lo, vcc_lo, 3
	s_mul_i32 vcc_lo, vcc_lo, s100
	s_lshl_b32 s101, s101, 8
	v_mov_b32_e32 v2, s101
	v_mov_b32_e32 v4, 1
	s_waitcnt vmcnt(0) lgkmcnt(0)
	global_atomic_add v5, v2, v4, s[98:99] sc0
	v_add_u32_e32 v3, 0x900, v2
	s_waitcnt vmcnt(0)
	v_readfirstlane_b32 s101, v5
	s_add_i32 s101, s101, 1
	s_cmp_eq_u32 s101, vcc_lo
	s_cbranch_scc0 .Lb3_poll_0
	v_mov_b32_e32 v6, 0x800
	global_atomic_add v5, v6, v4, s[98:99] sc0
	s_min_u32 vcc_lo, s3, 8
	s_mul_i32 vcc_lo, vcc_lo, s100
	s_waitcnt vmcnt(0)
	v_readfirstlane_b32 s101, v5
	s_add_i32 s101, s101, 1
	s_cmp_eq_u32 s101, vcc_lo
	s_cbranch_scc0 .Lb3_poll_0
	v_mov_b32_e32 v6, 0x900
	global_atomic_add v6, v4, s[98:99]
	global_atomic_add v6, v4, s[98:99] offset:256
	global_atomic_add v6, v4, s[98:99] offset:512
	global_atomic_add v6, v4, s[98:99] offset:768
	global_atomic_add v6, v4, s[98:99] offset:1024
	global_atomic_add v6, v4, s[98:99] offset:1280
	global_atomic_add v6, v4, s[98:99] offset:1536
	global_atomic_add v6, v4, s[98:99] offset:1792
.Lb3_poll_0:
	s_movk_i32 m0, 0x7fff
.Lb3_p_0:
	global_load_dword v5, v3, s[98:99] sc1
	s_waitcnt vmcnt(0)
	v_readfirstlane_b32 s101, v5
	s_cmp_ge_u32 s101, s100
	s_cbranch_scc1 .Lb3_ok_0
	s_sleep 1
	s_sub_u32 m0, m0, 1
	s_cmp_eq_u32 m0, 0
	s_cbranch_scc0 .Lb3_p_0
.Lb3_ok_0:
	buffer_inv sc1
	s_waitcnt vmcnt(0)
	s_branch .LBB0_182

.LBB0_226:
	s_getreg_b32 s0, hwreg(HW_REG_XCC_ID, 0, 4)
	s_and_b32 s9, s0, 15
	s_waitcnt vmcnt(0)
	s_waitcnt vmcnt(0)
	s_barrier
	s_and_saveexec_b64 s[0:1], s[52:53]
	v_readlane_b32 s24, v255, 22
	s_add_i32 s100, s100, 1
	s_cbranch_execz .LBB0_278
	v_readlane_b32 s98, v253, 2
	v_readlane_b32 s99, v253, 3
	s_nop 0
	s_add_u32 s98, s98, 0x7c000
	s_addc_u32 s99, s99, 0
	s_and_b32 s101, s2, 7
	s_sub_u32 vcc_lo, 7, s101
	s_add_u32 vcc_lo, vcc_lo, s3
	s_lshr_b32 vcc_lo, vcc_lo, 3
	s_mul_i32 vcc_lo, vcc_lo, s100
	s_lshl_b32 s101, s101, 8
	v_mov_b32_e32 v2, s101
	v_mov_b32_e32 v4, 1
	s_waitcnt vmcnt(0) lgkmcnt(0)
	global_atomic_add v5, v2, v4, s[98:99] sc0
	v_add_u32_e32 v3, 0x900, v2
	s_waitcnt vmcnt(0)
	v_readfirstlane_b32 s101, v5
	s_add_i32 s101, s101, 1
	s_cmp_eq_u32 s101, vcc_lo
	s_cbranch_scc0 .Lb3_poll_1
	v_mov_b32_e32 v6, 0x800
	global_atomic_add v5, v6, v4, s[98:99] sc0
	s_min_u32 vcc_lo, s3, 8
	s_mul_i32 vcc_lo, vcc_lo, s100
	s_waitcnt vmcnt(0)
	v_readfirstlane_b32 s101, v5
	s_add_i32 s101, s101, 1
	s_cmp_eq_u32 s101, vcc_lo
	s_cbranch_scc0 .Lb3_poll_1
	v_mov_b32_e32 v6, 0x900
	global_atomic_add v6, v4, s[98:99]
	global_atomic_add v6, v4, s[98:99] offset:256
	global_atomic_add v6, v4, s[98:99] offset:512
	global_atomic_add v6, v4, s[98:99] offset:768
	global_atomic_add v6, v4, s[98:99] offset:1024
	global_atomic_add v6, v4, s[98:99] offset:1280
	global_atomic_add v6, v4, s[98:99] offset:1536
	global_atomic_add v6, v4, s[98:99] offset:1792

.LBB0_292:
	s_getreg_b32 s0, hwreg(HW_REG_XCC_ID, 0, 4)
	s_and_b32 s9, s0, 15
	s_waitcnt vmcnt(0)
	v_readlane_b32 s52, v253, 4
	v_readlane_b32 s53, v253, 5
	s_barrier
	s_and_saveexec_b64 s[0:1], s[52:53]
	v_readlane_b32 s54, v255, 8
	v_readlane_b32 s55, v255, 9
	s_add_i32 s100, s100, 1
	s_cbranch_execz .LBB0_344
	v_readlane_b32 s98, v253, 2
	v_readlane_b32 s99, v253, 3
	s_nop 0
	s_add_u32 s98, s98, 0x7c000
	s_addc_u32 s99, s99, 0
	s_and_b32 s101, s2, 7
	s_sub_u32 vcc_lo, 7, s101
	s_add_u32 vcc_lo, vcc_lo, s3
	s_lshr_b32 vcc_lo, vcc_lo, 3
	s_mul_i32 vcc_lo, vcc_lo, s100
	s_lshl_b32 s101, s101, 8
	v_mov_b32_e32 v2, s101
	v_mov_b32_e32 v4, 1
	s_waitcnt vmcnt(0) lgkmcnt(0)
	global_atomic_add v5, v2, v4, s[98:99] sc0
	v_add_u32_e32 v3, 0x900, v2
	s_waitcnt vmcnt(0)
	v_readfirstlane_b32 s101, v5
	s_add_i32 s101, s101, 1
	s_cmp_eq_u32 s101, vcc_lo
	s_cbranch_scc0 .Lb3_poll_2
	v_mov_b32_e32 v6, 0x800
	global_atomic_add v5, v6, v4, s[98:99] sc0
	s_min_u32 vcc_lo, s3, 8
	s_mul_i32 vcc_lo, vcc_lo, s100
	s_waitcnt vmcnt(0)
	v_readfirstlane_b32 s101, v5
	s_add_i32 s101, s101, 1
	s_cmp_eq_u32 s101, vcc_lo
	s_cbranch_scc0 .Lb3_poll_2
	v_mov_b32_e32 v6, 0x900
	global_atomic_add v6, v4, s[98:99]
	global_atomic_add v6, v4, s[98:99] offset:256
	global_atomic_add v6, v4, s[98:99] offset:512
	global_atomic_add v6, v4, s[98:99] offset:768
	global_atomic_add v6, v4, s[98:99] offset:1024
	global_atomic_add v6, v4, s[98:99] offset:1280
	global_atomic_add v6, v4, s[98:99] offset:1536
	global_atomic_add v6, v4, s[98:99] offset:1792

.LBB0_369:
	s_getreg_b32 s0, hwreg(HW_REG_XCC_ID, 0, 4)
	s_and_b32 s9, s0, 15
	s_waitcnt vmcnt(0)
	s_waitcnt vmcnt(0)
	s_barrier
	s_and_saveexec_b64 s[0:1], s[52:53]
	s_add_i32 s100, s100, 1
	s_cbranch_execz .LBB0_421
	v_readlane_b32 s98, v253, 2
	v_readlane_b32 s99, v253, 3
	s_nop 0
	s_add_u32 s98, s98, 0x7c000
	s_addc_u32 s99, s99, 0
	s_and_b32 s101, s2, 7
	s_sub_u32 vcc_lo, 7, s101
	s_add_u32 vcc_lo, vcc_lo, s3
	s_lshr_b32 vcc_lo, vcc_lo, 3
	s_mul_i32 vcc_lo, vcc_lo, s100
	s_lshl_b32 s101, s101, 8
	v_mov_b32_e32 v2, s101
	v_mov_b32_e32 v4, 1
	s_waitcnt vmcnt(0) lgkmcnt(0)
	global_atomic_add v5, v2, v4, s[98:99] sc0
	v_add_u32_e32 v3, 0x900, v2
	s_waitcnt vmcnt(0)
	v_readfirstlane_b32 s101, v5
	s_add_i32 s101, s101, 1
	s_cmp_eq_u32 s101, vcc_lo
	s_cbranch_scc0 .Lb3_poll_3
	v_mov_b32_e32 v6, 0x800
	global_atomic_add v5, v6, v4, s[98:99] sc0
	s_min_u32 vcc_lo, s3, 8
	s_mul_i32 vcc_lo, vcc_lo, s100
	s_waitcnt vmcnt(0)
	v_readfirstlane_b32 s101, v5
	s_add_i32 s101, s101, 1
	s_cmp_eq_u32 s101, vcc_lo
	s_cbranch_scc0 .Lb3_poll_3
	v_mov_b32_e32 v6, 0x900
	global_atomic_add v6, v4, s[98:99]
	global_atomic_add v6, v4, s[98:99] offset:256
	global_atomic_add v6, v4, s[98:99] offset:512
	global_atomic_add v6, v4, s[98:99] offset:768
	global_atomic_add v6, v4, s[98:99] offset:1024
	global_atomic_add v6, v4, s[98:99] offset:1280
	global_atomic_add v6, v4, s[98:99] offset:1536
	global_atomic_add v6, v4, s[98:99] offset:1792

.LBB0_480:
	s_getreg_b32 s0, hwreg(HW_REG_XCC_ID, 0, 4)
	s_and_b32 s12, s0, 15
	s_waitcnt vmcnt(0)
	s_barrier
	s_and_saveexec_b64 s[0:1], s[52:53]
	s_add_i32 s100, s100, 1
	s_cbranch_execz .LBB0_532
	v_readlane_b32 s98, v253, 2
	v_readlane_b32 s99, v253, 3
	s_nop 0
	s_add_u32 s98, s98, 0x7c000
	s_addc_u32 s99, s99, 0
	s_and_b32 s101, s2, 7
	s_sub_u32 vcc_lo, 7, s101
	s_add_u32 vcc_lo, vcc_lo, s3
	s_lshr_b32 vcc_lo, vcc_lo, 3
	s_mul_i32 vcc_lo, vcc_lo, s100
	s_lshl_b32 s101, s101, 8
	v_mov_b32_e32 v2, s101
	v_mov_b32_e32 v4, 1
	s_waitcnt vmcnt(0) lgkmcnt(0)
	global_atomic_add v5, v2, v4, s[98:99] sc0
	v_add_u32_e32 v3, 0x900, v2
	s_waitcnt vmcnt(0)
	v_readfirstlane_b32 s101, v5
	s_add_i32 s101, s101, 1
	s_cmp_eq_u32 s101, vcc_lo
	s_cbranch_scc0 .Lb3_poll_4
	v_mov_b32_e32 v6, 0x800
	global_atomic_add v5, v6, v4, s[98:99] sc0
	s_min_u32 vcc_lo, s3, 8
	s_mul_i32 vcc_lo, vcc_lo, s100
	s_waitcnt vmcnt(0)
	v_readfirstlane_b32 s101, v5
	s_add_i32 s101, s101, 1
	s_cmp_eq_u32 s101, vcc_lo
	s_cbranch_scc0 .Lb3_poll_4
	v_mov_b32_e32 v6, 0x900
	global_atomic_add v6, v4, s[98:99]
	global_atomic_add v6, v4, s[98:99] offset:256
	global_atomic_add v6, v4, s[98:99] offset:512
	global_atomic_add v6, v4, s[98:99] offset:768
	global_atomic_add v6, v4, s[98:99] offset:1024
	global_atomic_add v6, v4, s[98:99] offset:1280
	global_atomic_add v6, v4, s[98:99] offset:1536
	global_atomic_add v6, v4, s[98:99] offset:1792

.LBB0_569:
	s_or_b64 exec, exec, s[0:1]
	s_getreg_b32 s0, hwreg(HW_REG_XCC_ID, 0, 4)
	s_and_b32 s12, s0, 15
	s_waitcnt vmcnt(0)
	s_barrier
	s_and_saveexec_b64 s[0:1], s[52:53]
	s_add_i32 s100, s100, 1
	s_cbranch_execz .LBB0_621
	v_readlane_b32 s98, v253, 2
	v_readlane_b32 s99, v253, 3
	s_nop 0
	s_add_u32 s98, s98, 0x7c000
	s_addc_u32 s99, s99, 0
	s_and_b32 s101, s2, 7
	s_sub_u32 vcc_lo, 7, s101
	s_add_u32 vcc_lo, vcc_lo, s3
	s_lshr_b32 vcc_lo, vcc_lo, 3
	s_mul_i32 vcc_lo, vcc_lo, s100
	s_lshl_b32 s101, s101, 8
	v_mov_b32_e32 v2, s101
	v_mov_b32_e32 v4, 1
	s_waitcnt vmcnt(0) lgkmcnt(0)
	global_atomic_add v5, v2, v4, s[98:99] sc0
	v_add_u32_e32 v3, 0x900, v2
	s_waitcnt vmcnt(0)
	v_readfirstlane_b32 s101, v5
	s_add_i32 s101, s101, 1
	s_cmp_eq_u32 s101, vcc_lo
	s_cbranch_scc0 .Lb3_poll_5
	v_mov_b32_e32 v6, 0x800
	global_atomic_add v5, v6, v4, s[98:99] sc0
	s_min_u32 vcc_lo, s3, 8
	s_mul_i32 vcc_lo, vcc_lo, s100
	s_waitcnt vmcnt(0)
	v_readfirstlane_b32 s101, v5
	s_add_i32 s101, s101, 1
	s_cmp_eq_u32 s101, vcc_lo
	s_cbranch_scc0 .Lb3_poll_5
	v_mov_b32_e32 v6, 0x900
	global_atomic_add v6, v4, s[98:99]
	global_atomic_add v6, v4, s[98:99] offset:256
	global_atomic_add v6, v4, s[98:99] offset:512
	global_atomic_add v6, v4, s[98:99] offset:768
	global_atomic_add v6, v4, s[98:99] offset:1024
	global_atomic_add v6, v4, s[98:99] offset:1280
	global_atomic_add v6, v4, s[98:99] offset:1536
	global_atomic_add v6, v4, s[98:99] offset:1792

.LBB0_691:
	s_getreg_b32 s0, hwreg(HW_REG_XCC_ID, 0, 4)
	s_and_b32 s10, s0, 15
	s_waitcnt vmcnt(0)
	s_barrier
	s_and_saveexec_b64 s[0:1], s[52:53]
	v_readlane_b32 s14, v255, 16
	v_readlane_b32 s15, v255, 17
	s_add_i32 s100, s100, 1
	s_cbranch_execz .LBB0_743
	v_readlane_b32 s98, v253, 2
	v_readlane_b32 s99, v253, 3
	s_nop 0
	s_add_u32 s98, s98, 0x7c000
	s_addc_u32 s99, s99, 0
	s_and_b32 s101, s2, 7
	s_sub_u32 vcc_lo, 7, s101
	s_add_u32 vcc_lo, vcc_lo, s3
	s_lshr_b32 vcc_lo, vcc_lo, 3
	s_mul_i32 vcc_lo, vcc_lo, s100
	s_lshl_b32 s101, s101, 8
	v_mov_b32_e32 v2, s101
	v_mov_b32_e32 v4, 1
	s_waitcnt vmcnt(0) lgkmcnt(0)
	global_atomic_add v5, v2, v4, s[98:99] sc0
	v_add_u32_e32 v3, 0x900, v2
	s_waitcnt vmcnt(0)
	v_readfirstlane_b32 s101, v5
	s_add_i32 s101, s101, 1
	s_cmp_eq_u32 s101, vcc_lo
	s_cbranch_scc0 .Lb3_poll_6
	v_mov_b32_e32 v6, 0x800
	global_atomic_add v5, v6, v4, s[98:99] sc0
	s_min_u32 vcc_lo, s3, 8
	s_mul_i32 vcc_lo, vcc_lo, s100
	s_waitcnt vmcnt(0)
	v_readfirstlane_b32 s101, v5
	s_add_i32 s101, s101, 1
	s_cmp_eq_u32 s101, vcc_lo
	s_cbranch_scc0 .Lb3_poll_6
	v_mov_b32_e32 v6, 0x900
	global_atomic_add v6, v4, s[98:99]
	global_atomic_add v6, v4, s[98:99] offset:256
	global_atomic_add v6, v4, s[98:99] offset:512
	global_atomic_add v6, v4, s[98:99] offset:768
	global_atomic_add v6, v4, s[98:99] offset:1024
	global_atomic_add v6, v4, s[98:99] offset:1280
	global_atomic_add v6, v4, s[98:99] offset:1536
	global_atomic_add v6, v4, s[98:99] offset:1792

.LBB0_866:
	s_getreg_b32 s0, hwreg(HW_REG_XCC_ID, 0, 4)
	s_and_b32 s10, s0, 15
	s_waitcnt vmcnt(0)
	s_waitcnt vmcnt(0)
	s_barrier
	s_and_saveexec_b64 s[0:1], s[52:53]
	v_readlane_b32 s14, v255, 14
	v_readlane_b32 s16, v255, 16
	v_readlane_b32 s15, v255, 15
	v_readlane_b32 s17, v255, 17
	s_add_i32 s100, s100, 1
	s_cbranch_execz .LBB0_918
	v_readlane_b32 s98, v253, 2
	v_readlane_b32 s99, v253, 3
	s_nop 0
	s_add_u32 s98, s98, 0x7c000
	s_addc_u32 s99, s99, 0
	s_and_b32 s101, s2, 7
	s_sub_u32 vcc_lo, 7, s101
	s_add_u32 vcc_lo, vcc_lo, s3
	s_lshr_b32 vcc_lo, vcc_lo, 3
	s_mul_i32 vcc_lo, vcc_lo, s100
	s_lshl_b32 s101, s101, 8
	v_mov_b32_e32 v2, s101
	v_mov_b32_e32 v4, 1
	s_waitcnt vmcnt(0) lgkmcnt(0)
	global_atomic_add v5, v2, v4, s[98:99] sc0
	v_add_u32_e32 v3, 0x900, v2
	s_waitcnt vmcnt(0)
	v_readfirstlane_b32 s101, v5
	s_add_i32 s101, s101, 1
	s_cmp_eq_u32 s101, vcc_lo
	s_cbranch_scc0 .Lb3_poll_7
	v_mov_b32_e32 v6, 0x800
	global_atomic_add v5, v6, v4, s[98:99] sc0
	s_min_u32 vcc_lo, s3, 8
	s_mul_i32 vcc_lo, vcc_lo, s100
	s_waitcnt vmcnt(0)
	v_readfirstlane_b32 s101, v5
	s_add_i32 s101, s101, 1
	s_cmp_eq_u32 s101, vcc_lo
	s_cbranch_scc0 .Lb3_poll_7
	v_mov_b32_e32 v6, 0x900
	global_atomic_add v6, v4, s[98:99]
	global_atomic_add v6, v4, s[98:99] offset:256
	global_atomic_add v6, v4, s[98:99] offset:512
	global_atomic_add v6, v4, s[98:99] offset:768
	global_atomic_add v6, v4, s[98:99] offset:1024
	global_atomic_add v6, v4, s[98:99] offset:1280
	global_atomic_add v6, v4, s[98:99] offset:1536
	global_atomic_add v6, v4, s[98:99] offset:1792

.LBB0_954:
	s_getreg_b32 s0, hwreg(HW_REG_XCC_ID, 0, 4)
	s_and_b32 s10, s0, 15
	s_waitcnt vmcnt(0)
	s_barrier
	s_and_saveexec_b64 s[0:1], s[52:53]
	v_readlane_b32 s28, v255, 14
	v_readlane_b32 s14, v255, 16
	v_readlane_b32 s29, v255, 15
	v_readlane_b32 s15, v255, 17
	s_add_i32 s100, s100, 1
	s_cbranch_execz .LBB0_1006
	v_readlane_b32 s98, v253, 2
	v_readlane_b32 s99, v253, 3
	s_nop 0
	s_add_u32 s98, s98, 0x7c000
	s_addc_u32 s99, s99, 0
	s_and_b32 s101, s2, 7
	s_sub_u32 vcc_lo, 7, s101
	s_add_u32 vcc_lo, vcc_lo, s3
	s_lshr_b32 vcc_lo, vcc_lo, 3
	s_mul_i32 vcc_lo, vcc_lo, s100
	s_lshl_b32 s101, s101, 8
	v_mov_b32_e32 v2, s101
	v_mov_b32_e32 v4, 1
	s_waitcnt vmcnt(0) lgkmcnt(0)
	global_atomic_add v5, v2, v4, s[98:99] sc0
	v_add_u32_e32 v3, 0x900, v2
	s_waitcnt vmcnt(0)
	v_readfirstlane_b32 s101, v5
	s_add_i32 s101, s101, 1
	s_cmp_eq_u32 s101, vcc_lo
	s_cbranch_scc0 .Lb3_poll_8
	v_mov_b32_e32 v6, 0x800
	global_atomic_add v5, v6, v4, s[98:99] sc0
	s_min_u32 vcc_lo, s3, 8
	s_mul_i32 vcc_lo, vcc_lo, s100
	s_waitcnt vmcnt(0)
	v_readfirstlane_b32 s101, v5
	s_add_i32 s101, s101, 1
	s_cmp_eq_u32 s101, vcc_lo
	s_cbranch_scc0 .Lb3_poll_8
	v_mov_b32_e32 v6, 0x900
	global_atomic_add v6, v4, s[98:99]
	global_atomic_add v6, v4, s[98:99] offset:256
	global_atomic_add v6, v4, s[98:99] offset:512
	global_atomic_add v6, v4, s[98:99] offset:768
	global_atomic_add v6, v4, s[98:99] offset:1024
	global_atomic_add v6, v4, s[98:99] offset:1280
	global_atomic_add v6, v4, s[98:99] offset:1536
	global_atomic_add v6, v4, s[98:99] offset:1792

.LBB0_1067:
	s_getreg_b32 s0, hwreg(HW_REG_XCC_ID, 0, 4)
	s_and_b32 s10, s0, 15
	s_waitcnt vmcnt(0)
	s_barrier
	s_and_saveexec_b64 s[0:1], s[52:53]
	v_readlane_b32 s22, v255, 16
	v_readlane_b32 s23, v255, 17
	s_add_i32 s100, s100, 1
	s_cbranch_execz .LBB0_1119
	v_readlane_b32 s98, v253, 2
	v_readlane_b32 s99, v253, 3
	s_nop 0
	s_add_u32 s98, s98, 0x7c000
	s_addc_u32 s99, s99, 0
	s_and_b32 s101, s2, 7
	s_sub_u32 vcc_lo, 7, s101
	s_add_u32 vcc_lo, vcc_lo, s3
	s_lshr_b32 vcc_lo, vcc_lo, 3
	s_mul_i32 vcc_lo, vcc_lo, s100
	s_lshl_b32 s101, s101, 8
	v_mov_b32_e32 v2, s101
	v_mov_b32_e32 v4, 1
	s_waitcnt vmcnt(0) lgkmcnt(0)
	global_atomic_add v5, v2, v4, s[98:99] sc0
	v_add_u32_e32 v3, 0x900, v2
	s_waitcnt vmcnt(0)
	v_readfirstlane_b32 s101, v5
	s_add_i32 s101, s101, 1
	s_cmp_eq_u32 s101, vcc_lo
	s_cbranch_scc0 .Lb3_poll_9
	v_mov_b32_e32 v6, 0x800
	global_atomic_add v5, v6, v4, s[98:99] sc0
	s_min_u32 vcc_lo, s3, 8
	s_mul_i32 vcc_lo, vcc_lo, s100
	s_waitcnt vmcnt(0)
	v_readfirstlane_b32 s101, v5
	s_add_i32 s101, s101, 1
	s_cmp_eq_u32 s101, vcc_lo
	s_cbranch_scc0 .Lb3_poll_9
	v_mov_b32_e32 v6, 0x900
	global_atomic_add v6, v4, s[98:99]
	global_atomic_add v6, v4, s[98:99] offset:256
	global_atomic_add v6, v4, s[98:99] offset:512
	global_atomic_add v6, v4, s[98:99] offset:768
	global_atomic_add v6, v4, s[98:99] offset:1024
	global_atomic_add v6, v4, s[98:99] offset:1280
	global_atomic_add v6, v4, s[98:99] offset:1536
	global_atomic_add v6, v4, s[98:99] offset:1792

.LBB0_1156:
	s_getreg_b32 s0, hwreg(HW_REG_XCC_ID, 0, 4)
	s_and_b32 s4, s0, 15
	s_waitcnt vmcnt(0)
	s_waitcnt vmcnt(0)
	s_barrier
	s_and_saveexec_b64 s[0:1], s[52:53]
	s_add_i32 s100, s100, 1
	s_cbranch_execz .LBB0_1208
	v_readlane_b32 s98, v253, 2
	v_readlane_b32 s99, v253, 3
	s_nop 0
	s_add_u32 s98, s98, 0x7c000
	s_addc_u32 s99, s99, 0
	s_and_b32 s101, s2, 7
	s_sub_u32 vcc_lo, 7, s101
	s_add_u32 vcc_lo, vcc_lo, s3
	s_lshr_b32 vcc_lo, vcc_lo, 3
	s_mul_i32 vcc_lo, vcc_lo, s100
	s_lshl_b32 s101, s101, 8
	v_mov_b32_e32 v2, s101
	v_mov_b32_e32 v4, 1
	s_waitcnt vmcnt(0) lgkmcnt(0)
	global_atomic_add v5, v2, v4, s[98:99] sc0
	v_add_u32_e32 v3, 0x900, v2
	s_waitcnt vmcnt(0)
	v_readfirstlane_b32 s101, v5
	s_add_i32 s101, s101, 1
	s_cmp_eq_u32 s101, vcc_lo
	s_cbranch_scc0 .Lb3_poll_10
	v_mov_b32_e32 v6, 0x800
	global_atomic_add v5, v6, v4, s[98:99] sc0
	s_min_u32 vcc_lo, s3, 8
	s_mul_i32 vcc_lo, vcc_lo, s100
	s_waitcnt vmcnt(0)
	v_readfirstlane_b32 s101, v5
	s_add_i32 s101, s101, 1
	s_cmp_eq_u32 s101, vcc_lo
	s_cbranch_scc0 .Lb3_poll_10
	v_mov_b32_e32 v6, 0x900
	global_atomic_add v6, v4, s[98:99]
	global_atomic_add v6, v4, s[98:99] offset:256
	global_atomic_add v6, v4, s[98:99] offset:512
	global_atomic_add v6, v4, s[98:99] offset:768
	global_atomic_add v6, v4, s[98:99] offset:1024
	global_atomic_add v6, v4, s[98:99] offset:1280
	global_atomic_add v6, v4, s[98:99] offset:1536
	global_atomic_add v6, v4, s[98:99] offset:1792

.LBB0_1337:
	v_readlane_b32 s34, v255, 14
	v_readlane_b32 s22, v255, 16
	s_and_b64 vcc, exec, s[38:39]
	s_mov_b64 s[0:1], -1
	v_readlane_b32 s35, v255, 15
	v_readlane_b32 s23, v255, 17
	s_cbranch_vccnz .LBB0_1391
	s_getreg_b32 s0, hwreg(HW_REG_XCC_ID, 0, 4)
	s_and_b32 s10, s0, 15
	s_waitcnt vmcnt(0)
	s_barrier
	s_and_saveexec_b64 s[0:1], s[52:53]
	s_add_i32 s100, s100, 1
	s_cbranch_execz .LBB0_1390
	v_readlane_b32 s98, v253, 2
	v_readlane_b32 s99, v253, 3
	s_nop 0
	s_add_u32 s98, s98, 0x7c000
	s_addc_u32 s99, s99, 0
	s_and_b32 s101, s2, 7
	s_sub_u32 vcc_lo, 7, s101
	s_add_u32 vcc_lo, vcc_lo, s3
	s_lshr_b32 vcc_lo, vcc_lo, 3
	s_mul_i32 vcc_lo, vcc_lo, s100
	s_lshl_b32 s101, s101, 8
	v_mov_b32_e32 v2, s101
	v_mov_b32_e32 v4, 1
	s_waitcnt vmcnt(0) lgkmcnt(0)
	global_atomic_add v5, v2, v4, s[98:99] sc0
	v_add_u32_e32 v3, 0x900, v2
	s_waitcnt vmcnt(0)
	v_readfirstlane_b32 s101, v5
	s_add_i32 s101, s101, 1
	s_cmp_eq_u32 s101, vcc_lo
	s_cbranch_scc0 .Lb3_poll_11
	v_mov_b32_e32 v6, 0x800
	global_atomic_add v5, v6, v4, s[98:99] sc0
	s_min_u32 vcc_lo, s3, 8
	s_mul_i32 vcc_lo, vcc_lo, s100
	s_waitcnt vmcnt(0)
	v_readfirstlane_b32 s101, v5
	s_add_i32 s101, s101, 1
	s_cmp_eq_u32 s101, vcc_lo
	s_cbranch_scc0 .Lb3_poll_11
	v_mov_b32_e32 v6, 0x900
	global_atomic_add v6, v4, s[98:99]
	global_atomic_add v6, v4, s[98:99] offset:256
	global_atomic_add v6, v4, s[98:99] offset:512
	global_atomic_add v6, v4, s[98:99] offset:768
	global_atomic_add v6, v4, s[98:99] offset:1024
	global_atomic_add v6, v4, s[98:99] offset:1280
	global_atomic_add v6, v4, s[98:99] offset:1536
	global_atomic_add v6, v4, s[98:99] offset:1792

	.amdhsa_kernel _Z6mk_fwd4Args
		.amdhsa_group_segment_fixed_size 0
		.amdhsa_private_segment_fixed_size 0
		.amdhsa_kernarg_size 416
		.amdhsa_user_sgpr_count 2
		.amdhsa_user_sgpr_dispatch_ptr 0
		.amdhsa_user_sgpr_queue_ptr 0
		.amdhsa_user_sgpr_kernarg_segment_ptr 1
		.amdhsa_user_sgpr_dispatch_id 0
		.amdhsa_user_sgpr_kernarg_preload_length 0
		.amdhsa_user_sgpr_kernarg_preload_offset 0
		.amdhsa_user_sgpr_private_segment_size 0
		.amdhsa_uses_dynamic_stack 0
		.amdhsa_enable_private_segment 0
		.amdhsa_system_sgpr_workgroup_id_x 1
		.amdhsa_system_sgpr_workgroup_id_y 0
		.amdhsa_system_sgpr_workgroup_id_z 0
		.amdhsa_system_sgpr_workgroup_info 0
		.amdhsa_system_vgpr_workitem_id 0
		.amdhsa_next_free_vgpr 256
		.amdhsa_next_free_sgpr 102
		.amdhsa_accum_offset 256
		.amdhsa_reserve_vcc 1
		.amdhsa_float_round_mode_32 0
		.amdhsa_float_round_mode_16_64 0
		.amdhsa_float_denorm_mode_32 3
		.amdhsa_float_denorm_mode_16_64 3
		.amdhsa_dx10_clamp 1
		.amdhsa_ieee_mode 1
		.amdhsa_fp16_overflow 0
		.amdhsa_tg_split 0
		.amdhsa_exception_fp_ieee_invalid_op 0
		.amdhsa_exception_fp_denorm_src 0
		.amdhsa_exception_fp_ieee_div_zero 0
		.amdhsa_exception_fp_ieee_overflow 0
		.amdhsa_exception_fp_ieee_underflow 0
		.amdhsa_exception_fp_ieee_inexact 0
		.amdhsa_exception_int_div_zero 0
	.end_amdhsa_kernel

amdhsa.kernels:
  - .agpr_count:     0
    .args:
      - .offset:         0
        .size:           160
        .value_kind:     by_value
      - .offset:         160
        .size:           4
        .value_kind:     hidden_block_count_x
      - .offset:         164
        .size:           4
        .value_kind:     hidden_block_count_y
      - .offset:         168
        .size:           4
        .value_kind:     hidden_block_count_z
      - .offset:         172
        .size:           2
        .value_kind:     hidden_group_size_x
      - .offset:         174
        .size:           2
        .value_kind:     hidden_group_size_y
      - .offset:         176
        .size:           2
        .value_kind:     hidden_group_size_z
      - .offset:         178
        .size:           2
        .value_kind:     hidden_remainder_x
      - .offset:         180
        .size:           2
        .value_kind:     hidden_remainder_y
      - .offset:         182
        .size:           2
        .value_kind:     hidden_remainder_z
      - .offset:         200
        .size:           8
        .value_kind:     hidden_global_offset_x
      - .offset:         208
        .size:           8
        .value_kind:     hidden_global_offset_y
      - .offset:         216
        .size:           8
        .value_kind:     hidden_global_offset_z
      - .offset:         224
        .size:           2
        .value_kind:     hidden_grid_dims
      - .offset:         280
        .size:           4
        .value_kind:     hidden_dynamic_lds_size
    .group_segment_fixed_size: 0
    .kernarg_segment_align: 8
    .kernarg_segment_size: 416
    .language:       OpenCL C
    .language_version:
      - 2
      - 0
    .max_flat_workgroup_size: 512
    .name:           _Z6mk_fwd4Args
    .private_segment_fixed_size: 0
    .sgpr_count:     108
    .sgpr_spill_count: 179
    .symbol:         _Z6mk_fwd4Args.kd
    .uniform_work_group_size: 1
    .uses_dynamic_stack: false
    .vgpr_count:     256
    .vgpr_spill_count: 0
    .wavefront_size: 64
